# attention first sub-tile: deeper score-operand prefetch (third K/Q pair requested up front in two idle fragment slots, fourth K one MFMA pair earlier), counted waits re-derived
# baseline (speedup 1.0000x reference)
; #define LAS __attribute__((address_space(3)))
; __device__ __forceinline__ void dattn_unit(LAS unsigned char* lds, int b, int h, int qb, const bf16* Q, const bf16* K, const bf16* V, bf16* YB, float lam, const float* subg, float oml, int tid) {
;     ...
;                 for (int ks = 0; ks < 4; ++ks) { bf16x8 ka2 = ka, kb2 = kb, qa2 = qa, qb2 = qb;
;                     if (ks < 3) { ka2 = *(const LAS bf16x8*)(kp + (ks + 1) * 16); kb2 = *(const LAS bf16x8*)(kp + 64 * 72 + (ks + 1) * 16); qa2 = qsp[(ks + 1) * 64]; qb2 = qsp[(4 + ks + 1) * 64];
;                         __builtin_amdgcn_sched_group_barrier(0x100, 4, 0); }
;                     s0 = __builtin_amdgcn_mfma_f32_32x32x16_bf16(ka, qa, s0, 0, 0, 0);
;                     s1 = __builtin_amdgcn_mfma_f32_32x32x16_bf16(kb, qb, s1, 0, 0, 0);
;                     __builtin_amdgcn_sched_group_barrier(0x008, 2, 0);
;                     ka = ka2; kb = kb2; qa = qa2; qb = qb2; }
;             }
;             if (need_bm) { const LAS float* gb = tab + (159 - (q - (kvbase + 32 * sub + 4 * hi)));
; #pragma unroll
;                 for (int r = 0; r < 16; ++r) { const float bv = gb[(r & 3) + 8 * (r >> 2)]; s0[r] += bv; s1[r] += bv; } }
;     ...
;             for (int cb = 0; cb < 4; ++cb) { const LAS bf16* vp = Vt + (32 * cb + ql) * 72 + 32 * sub + 4 * hi;
;                 const v2u a0 = *(const LAS v2u*)(vp), a1 = *(const LAS v2u*)(vp + 8), a2 = *(const LAS v2u*)(vp + 16), a3 = *(const LAS v2u*)(vp + 24);
.Lqk_diag0:
	s_waitcnt lgkmcnt(3)
	v_mfma_f32_32x32x16_bf16 v[128:143], v[204:207], v[222:225], v[128:143]
	s_waitcnt lgkmcnt(2)
	v_mfma_f32_32x32x16_bf16 v[144:159], v[200:203], v[230:233], v[144:159]
	s_waitcnt lgkmcnt(0)
	v_mfma_f32_32x32x16_bf16 v[128:143], v[226:229], v[234:237], v[128:143]
	v_add_u32_e32 v200, s57, v198
	v_add_u32_e32 v212, 0x1227c, v200
	v_add_u32_e32 v214, 0x12284, v200
	v_add_u32_e32 v218, 0x1229c, v200
	v_add_u32_e32 v220, 0x122a4, v200
	v_add_u32_e32 v201, 0x122bc, v200
	v_add_u32_e32 v202, 0x122c4, v200
	v_add_u32_e32 v204, 0x122dc, v200
	v_add_u32_e32 v206, 0x122e4, v200
	ds_read2_b32 v[200:201], v201 offset1:1
	ds_read2_b32 v[202:203], v202 offset1:1
	ds_read2_b32 v[204:205], v204 offset1:1
	ds_read2_b32 v[206:207], v206 offset1:1
	ds_read2_b32 v[212:213], v212 offset1:1
	ds_read2_b32 v[214:215], v214 offset1:1
	ds_read2_b32 v[218:219], v218 offset1:1
	ds_read2_b32 v[220:221], v220 offset1:1
	s_waitcnt lgkmcnt(4)
	v_pk_add_f32 v[158:159], v[158:159], v[206:207]
	v_pk_add_f32 v[156:157], v[156:157], v[204:205]
	v_pk_add_f32 v[154:155], v[154:155], v[202:203]
	v_pk_add_f32 v[152:153], v[152:153], v[200:201]
	s_waitcnt lgkmcnt(0)
	v_pk_add_f32 v[150:151], v[150:151], v[220:221]
	v_pk_add_f32 v[148:149], v[148:149], v[218:219]
	v_pk_add_f32 v[146:147], v[146:147], v[214:215]
	v_pk_add_f32 v[144:145], v[144:145], v[212:213]
	v_pk_add_f32 v[142:143], v[142:143], v[206:207]
	v_pk_add_f32 v[140:141], v[140:141], v[204:205]
	v_pk_add_f32 v[138:139], v[138:139], v[202:203]
	v_pk_add_f32 v[136:137], v[136:137], v[200:201]
	v_pk_add_f32 v[134:135], v[134:135], v[220:221]
	v_pk_add_f32 v[132:133], v[132:133], v[218:219]
	v_pk_add_f32 v[130:131], v[130:131], v[214:215]
	v_pk_add_f32 v[128:129], v[128:129], v[212:213]
	v_add3_u32 v219, s38, v193, v192
	ds_read_b128 v[228:231], v219 offset:23040
	ds_read_b128 v[232:235], v219 offset:23072
	ds_read_b128 v[236:239], v219 offset:27648
	ds_read_b128 v[240:243], v219 offset:27680
	ds_read_b128 v[212:215], v219 offset:32256
	ds_read_b128 v[220:223], v219 offset:18432
	s_branch .Lsm0_0

; #define LAS __attribute__((address_space(3)))
; __device__ __forceinline__ void dattn_unit(LAS unsigned char* lds, int b, int h, int qb, const bf16* Q, const bf16* K, const bf16* V, bf16* YB, float lam, const float* subg, float oml, int tid) {
;     ...
;         if (t + 1 < NT) { const size_t adv = (size_t)(t + 1) * 64 * 1024; kr0 = *(const v4u*)(kg + adv); kr1 = *(const v4u*)(kg + adv + 64); vr0 = *(const v4u*)(vg + adv); vr1 = *(const v4u*)(vg + adv + 8); }
;         const LAS bf16* Ks = (const LAS bf16*)(lds + (t & 1) * AT_BUF + AT_KS); const LAS bf16* Vt = (const LAS bf16*)(lds + (t & 1) * AT_BUF + AT_VT);
;         const int kvbase = t * 64;
;         if (kvbase <= qmax) {
;     ...
; #pragma unroll
;         for (int sub = 0; sub < 2; ++sub) {
;             if (kvbase + 32 * sub > qmax) continue;
;             const bool need_bm = kvbase + 32 * sub + 31 + 113 > qmin;
;             LAS bf16x8* qsp = qs; asm volatile("" : "+v"(qsp));
;             f32x16 s0, s1;
; #pragma unroll
;             for (int r = 0; r < 16; ++r) { s0[r] = -mref[0]; s1[r] = -mref[1]; }
;             {
;                 const LAS bf16* kp = Ks + (32 * sub + ql) * 72 + hi * 8;
;                 bf16x8 ka = *(const LAS bf16x8*)kp, kb = *(const LAS bf16x8*)(kp + 64 * 72), qa = qsp[0], qb = qsp[4 * 64];
;                 __builtin_amdgcn_sched_group_barrier(0x100, 4, 0);
; #pragma unroll
;                 for (int ks = 0; ks < 4; ++ks) { bf16x8 ka2 = ka, kb2 = kb, qa2 = qa, qb2 = qb;
;                     if (ks < 3) { ka2 = *(const LAS bf16x8*)(kp + (ks + 1) * 16); kb2 = *(const LAS bf16x8*)(kp + 64 * 72 + (ks + 1) * 16); qa2 = qsp[(ks + 1) * 64]; qb2 = qsp[(4 + ks + 1) * 64];
;                         __builtin_amdgcn_sched_group_barrier(0x100, 4, 0); }
;                     s0 = __builtin_amdgcn_mfma_f32_32x32x16_bf16(ka, qa, s0, 0, 0, 0);
;                     s1 = __builtin_amdgcn_mfma_f32_32x32x16_bf16(kb, qb, s1, 0, 0, 0);
;                     __builtin_amdgcn_sched_group_barrier(0x008, 2, 0);
;                     ka = ka2; kb = kb2; qa = qa2; qb = qb2; }
;             }
.LBB0_227:
	v_lshl_add_u64 v[128:129], v[184:185], 0, s[98:99]
	v_lshl_add_u64 v[130:131], v[182:183], 0, s[100:101]
	global_load_dwordx4 v[168:171], v[128:129], off
	global_load_dwordx4 v[172:175], v[128:129], off offset:128
	s_add_i32 s18, s58, 0xffffff50
	global_load_dwordx4 v[164:167], v[130:131], off
	global_load_dwordx4 v[160:163], v[130:131], off offset:16
	s_cmp_gt_i32 s18, s35
	s_cbranch_scc1 .LBB0_226
	s_bitcmp1_b32 s59, 0
	s_cselect_b32 s18, 0x9000, 0
	s_add_i32 s38, s18, 0
	v_add3_u32 v199, s38, v208, v192
	ds_read_b128 v[138:141], v199
	ds_read_b128 v[200:203], v199 offset:9216
	ds_read_b128 v[204:207], v189
	ds_read_b128 v[218:221], v189 offset:4096
	ds_read_b128 v[222:225], v199 offset:32
	ds_read_b128 v[226:229], v199 offset:9248
	ds_read_b128 v[230:233], v189 offset:1024
	ds_read_b128 v[234:237], v189 offset:5120
	ds_read_b128 v[212:215], v199 offset:64
	ds_read_b128 v[238:241], v189 offset:2048
	v_xor_b32_e32 v144, 0x80000000, v190
	v_xor_b32_e32 v128, 0x80000000, v191
	v_mov_b32_e32 v145, v144
	v_mov_b64_e32 v[146:147], v[144:145]
	v_mov_b64_e32 v[148:149], v[144:145]
	v_mov_b64_e32 v[150:151], v[144:145]
	v_mov_b64_e32 v[152:153], v[144:145]
	v_mov_b64_e32 v[154:155], v[144:145]
	v_mov_b64_e32 v[156:157], v[144:145]
	v_mov_b64_e32 v[158:159], v[144:145]
	v_mov_b32_e32 v129, v128
	v_mov_b64_e32 v[130:131], v[128:129]
	v_mov_b64_e32 v[132:133], v[128:129]
	v_mov_b64_e32 v[134:135], v[128:129]
	v_mov_b64_e32 v[136:137], v[128:129]
	s_waitcnt lgkmcnt(7)
	v_mfma_f32_32x32x16_bf16 v[144:159], v[138:141], v[204:207], v[144:159]
	v_mov_b64_e32 v[142:143], v[128:129]
	v_mov_b64_e32 v[138:139], v[128:129]
	v_mov_b64_e32 v[140:141], v[128:129]
	s_sub_i32 s18, s58, 32
	s_cmp_le_i32 s18, s31
	s_waitcnt lgkmcnt(6)
	v_mfma_f32_32x32x16_bf16 v[128:143], v[200:203], v[218:221], v[128:143]
	ds_read_b128 v[204:207], v199 offset:9280
	ds_read_b128 v[200:203], v199 offset:96
	s_waitcnt lgkmcnt(5)
	v_mfma_f32_32x32x16_bf16 v[144:159], v[222:225], v[230:233], v[144:159]
	ds_read_b128 v[222:225], v189 offset:6144
	s_waitcnt lgkmcnt(5)
	v_mfma_f32_32x32x16_bf16 v[128:143], v[226:229], v[234:237], v[128:143]
	ds_read_b128 v[230:233], v189 offset:3072
	ds_read_b128 v[226:229], v199 offset:9312
	ds_read_b128 v[234:237], v189 offset:7168
	s_waitcnt lgkmcnt(6)
	v_mfma_f32_32x32x16_bf16 v[144:159], v[212:215], v[238:241], v[144:159]
	s_cbranch_scc0 .Lqk_diag0
	s_waitcnt lgkmcnt(2)
	v_mfma_f32_32x32x16_bf16 v[144:159], v[200:203], v[230:233], v[144:159]
	v_add3_u32 v219, s38, v193, v192
	ds_read_b128 v[212:215], v219 offset:32256
	v_mfma_f32_32x32x16_bf16 v[128:143], v[204:207], v[222:225], v[128:143]
	ds_read_b128 v[220:223], v219 offset:18432
	s_waitcnt lgkmcnt(2)
	v_mfma_f32_32x32x16_bf16 v[128:143], v[226:229], v[234:237], v[128:143]
	ds_read_b128 v[228:231], v219 offset:23040
	ds_read_b128 v[232:235], v219 offset:23072
	ds_read_b128 v[236:239], v219 offset:27648
	ds_read_b128 v[240:243], v219 offset:27680
	s_nop 1
